# prologue x->bf16 conversion loop: four row-quarter loads issued together one row ahead (register double buffer, counted wait) instead of load-wait x4 per row
# speedup vs baseline: 1.0079x; 1.0079x over previous
.LBB0_26:
	s_or_b64 exec, exec, s[6:7]
	s_cmpk_gt_i32 s1, 0x3fff
	s_cbranch_scc1 .LBB0_31
	v_readlane_b32 s10, v251, 7
	v_readlane_b32 s11, v251, 8
	s_load_dwordx2 s[6:7], s[10:11], 0x0
	s_load_dwordx2 s[14:15], s[10:11], 0xc8
	s_ashr_i32 s8, s3, 31
	s_ashr_i32 s9, s20, 31
	s_add_u32 s12, s3, s20
	s_addc_u32 s13, s8, s9
	s_lshl_b64 s[8:9], s[12:13], 6
	s_waitcnt lgkmcnt(0)
	s_add_u32 s8, s14, s8
	v_lshlrev_b32_e32 v6, 2, v15
	v_mov_b32_e32 v7, 0
	s_addc_u32 s9, s15, s9
	v_lshl_add_u64 v[0:1], s[8:9], 0, v[6:7]
	s_mov_b64 s[8:9], 0x15600000
	s_ashr_i32 s51, s50, 31
	v_lshl_add_u64 v[0:1], v[0:1], 0, s[8:9]
	s_lshl_b64 s[8:9], s[50:51], 6
	s_lshl_b64 s[10:11], s[12:13], 11
	s_add_u32 s10, s14, s10
	v_lshlrev_b32_e32 v6, 3, v15
	s_addc_u32 s11, s15, s11
	v_lshl_add_u64 v[2:3], s[10:11], 0, v[6:7]
	s_mov_b64 s[10:11], 0xa600400
	v_lshl_add_u64 v[2:3], v[2:3], 0, s[10:11]
	s_lshl_b64 s[10:11], s[50:51], 11
	s_lshl_b64 s[12:13], s[12:13], 12
	s_add_u32 s6, s6, s12
	v_mbcnt_lo_u32_b32 v5, -1, 0
	v_lshlrev_b32_e32 v6, 4, v15
	s_addc_u32 s7, s7, s13
	v_mbcnt_hi_u32_b32 v5, -1, v5
	v_lshl_add_u64 v[6:7], s[6:7], 0, v[6:7]
	s_mov_b64 s[6:7], 0xc00
	v_and_b32_e32 v8, 64, v5
	v_cmp_gt_u32_e32 vcc, 16, v15
	v_cmp_eq_u32_e64 s[4:5], 0, v15
	v_lshl_add_u64 v[6:7], v[6:7], 0, s[6:7]
	s_lshl_b64 s[12:13], s[50:51], 12
	v_add_u32_e32 v8, 64, v8
	v_xor_b32_e32 v9, 1, v5
	v_xor_b32_e32 v10, 2, v5
	v_xor_b32_e32 v11, 4, v5
	v_xor_b32_e32 v12, 8, v5
	v_xor_b32_e32 v13, 16, v5
	v_xor_b32_e32 v16, 32, v5
	s_mov_b32 s14, s1
	s_waitcnt lgkmcnt(0)
	global_load_dwordx4 v[36:39], v[6:7], off offset:-3072
	global_load_dwordx4 v[40:43], v[6:7], off offset:-2048
	global_load_dwordx4 v[44:47], v[6:7], off offset:-1024
	global_load_dwordx4 v[48:51], v[6:7], off
	s_waitcnt vmcnt(0)
	s_branch .Lxc_body
.LBB0_28:
	s_or_b64 exec, exec, s[6:7]
	s_add_i32 s14, s14, s50
	v_lshl_add_u64 v[0:1], v[0:1], 0, s[8:9]
	v_lshl_add_u64 v[2:3], v[2:3], 0, s[10:11]
	s_cmpk_gt_i32 s14, 0x3fff
	s_cbranch_scc1 .LBB0_31
.LBB0_29:
	s_waitcnt vmcnt(5)
.Lxc_body:
	s_waitcnt lgkmcnt(0)
	v_mov_b64_e32 v[52:53], v[36:37]
	v_mov_b64_e32 v[54:55], v[38:39]
	v_mov_b64_e32 v[56:57], v[40:41]
	v_mov_b64_e32 v[58:59], v[42:43]
	v_mov_b64_e32 v[60:61], v[44:45]
	v_mov_b64_e32 v[62:63], v[46:47]
	v_mov_b64_e32 v[64:65], v[48:49]
	v_mov_b64_e32 v[66:67], v[50:51]
	v_lshl_add_u64 v[6:7], v[6:7], 0, s[12:13]
	s_add_i32 s6, s14, s50
	s_cmpk_gt_i32 s6, 0x3fff
	s_cbranch_scc1 .Lxc_nold
	global_load_dwordx4 v[36:39], v[6:7], off offset:-3072
	global_load_dwordx4 v[40:43], v[6:7], off offset:-2048
	global_load_dwordx4 v[44:47], v[6:7], off offset:-1024
	global_load_dwordx4 v[48:51], v[6:7], off
.Lxc_nold:
	v_cvt_pk_bf16_f32 v22, v52, v53
	v_cvt_pk_bf16_f32 v23, v54, v55
	global_store_dwordx2 v[2:3], v[22:23], off offset:-1024
	v_lshlrev_b32_e32 v28, 16, v22
	v_and_b32_e32 v22, 0xffff0000, v22
	v_lshlrev_b32_e32 v29, 16, v23
	v_and_b32_e32 v23, 0xffff0000, v23
	v_mul_f32_e32 v22, v22, v22
	v_mul_f32_e32 v23, v23, v23
	v_cvt_pk_bf16_f32 v24, v56, v57
	v_cvt_pk_bf16_f32 v25, v58, v59
	v_fmac_f32_e32 v22, v28, v28
	v_fmac_f32_e32 v23, v29, v29
	global_store_dwordx2 v[2:3], v[24:25], off offset:-512
	v_add_f32_e32 v22, v22, v23
	v_lshlrev_b32_e32 v23, 16, v24
	v_and_b32_e32 v24, 0xffff0000, v24
	v_lshlrev_b32_e32 v28, 16, v25
	v_and_b32_e32 v25, 0xffff0000, v25
	v_mul_f32_e32 v24, v24, v24
	v_mul_f32_e32 v25, v25, v25
	v_fmac_f32_e32 v24, v23, v23
	v_fmac_f32_e32 v25, v28, v28
	v_cvt_pk_bf16_f32 v26, v60, v61
	v_add_f32_e32 v23, v24, v25
	v_cvt_pk_bf16_f32 v27, v62, v63
	global_store_dwordx2 v[2:3], v[26:27], off
	v_add_f32_e32 v22, v22, v23
	v_lshlrev_b32_e32 v23, 16, v26
	v_and_b32_e32 v24, 0xffff0000, v26
	v_and_b32_e32 v26, 0xffff0000, v27
	v_lshlrev_b32_e32 v25, 16, v27
	v_mul_f32_e32 v24, v24, v24
	v_mul_f32_e32 v26, v26, v26
	v_fmac_f32_e32 v24, v23, v23
	v_fmac_f32_e32 v26, v25, v25
	v_add_f32_e32 v23, v24, v26
	v_add_f32_e32 v24, v22, v23
	v_cvt_pk_bf16_f32 v22, v64, v65
	v_cvt_pk_bf16_f32 v23, v66, v67
	v_cmp_lt_i32_e64 s[6:7], v9, v8
	v_and_b32_e32 v19, 0xffff0000, v22
	v_and_b32_e32 v21, 0xffff0000, v23
	v_lshlrev_b32_e32 v18, 16, v22
	v_lshlrev_b32_e32 v20, 16, v23
	v_mul_f32_e32 v19, v19, v19
	v_mul_f32_e32 v21, v21, v21
	v_fmac_f32_e32 v19, v18, v18
	v_fmac_f32_e32 v21, v20, v20
	v_cndmask_b32_e64 v17, v5, v9, s[6:7]
	v_add_f32_e32 v18, v19, v21
	v_lshlrev_b32_e32 v17, 2, v17
	v_add_f32_e32 v18, v24, v18
	ds_bpermute_b32 v17, v17, v18
	v_cmp_lt_i32_e64 s[6:7], v10, v8
	global_store_dwordx2 v[2:3], v[22:23], off offset:512
	s_waitcnt lgkmcnt(0)
	v_add_f32_e32 v17, v18, v17
	v_cndmask_b32_e64 v19, v5, v10, s[6:7]
	v_lshlrev_b32_e32 v19, 2, v19
	ds_bpermute_b32 v18, v19, v17
	v_cmp_lt_i32_e64 s[6:7], v11, v8
	s_waitcnt lgkmcnt(0)
	v_add_f32_e32 v17, v17, v18
	v_cndmask_b32_e64 v19, v5, v11, s[6:7]
	v_lshlrev_b32_e32 v19, 2, v19
	ds_bpermute_b32 v18, v19, v17
	v_cmp_lt_i32_e64 s[6:7], v12, v8
	s_waitcnt lgkmcnt(0)
	v_add_f32_e32 v17, v17, v18
	v_cndmask_b32_e64 v19, v5, v12, s[6:7]
	v_lshlrev_b32_e32 v19, 2, v19
	ds_bpermute_b32 v18, v19, v17
	v_cmp_lt_i32_e64 s[6:7], v13, v8
	s_waitcnt lgkmcnt(0)
	v_add_f32_e32 v17, v17, v18
	v_cndmask_b32_e64 v19, v5, v13, s[6:7]
	v_lshlrev_b32_e32 v19, 2, v19
	ds_bpermute_b32 v18, v19, v17
	v_cmp_lt_i32_e64 s[6:7], v16, v8
	s_waitcnt lgkmcnt(0)
	v_add_f32_e32 v17, v17, v18
	v_cndmask_b32_e64 v19, v5, v16, s[6:7]
	v_lshlrev_b32_e32 v18, 2, v19
	ds_bpermute_b32 v18, v18, v17
	s_and_saveexec_b64 s[6:7], vcc
	s_cbranch_execz .LBB0_28
	s_waitcnt lgkmcnt(0)
	v_add_f32_e32 v17, v17, v18
	v_cndmask_b32_e64 v17, 0, v17, s[4:5]
	global_store_dword v[0:1], v17, off
	s_branch .LBB0_28
